# EpiUp (silu*up) epilogue hand-rescheduled: 4 interleaved chains per row, no s_nop padding, fewer VALU ops
# speedup vs baseline: 1.0194x; 1.0079x over previous
; #define LAS __attribute__((address_space(3)))
; DI unsigned pkh2(float a, float b) { typedef _Float16 h2 __attribute__((ext_vector_type(2))); h2 v; v[0] = (_Float16)a; v[1] = (_Float16)b; return __builtin_bit_cast(unsigned, v); }
; DI float sigmoidf_(float v) { return __builtin_amdgcn_rcpf(1.0f + __builtin_amdgcn_exp2f(-1.4426950408889634f * v)); }
;   DI void operator()(const f32x4 (&acc)[2][2][4][2], const pg8::Unit& u, int wr, int wc, int fr, int fq, LAS unsigned char* lds, int ui, int wid) const {
;     const int colg = u.pn * 256 + wc * 32 + 8 * fq, hcol = u.pn * 128 + wc * 32 + 8 * fq;
;     f32x4 c1g[2], c2g[2], c1u[2], c2u[2];
;     int fq_ = fq, fr_ = fr; asm volatile("" : "+v"(fq_), "+v"(fr_));
;     const LAS float* cl = (const LAS float*)(lds + 139264 + (ui & 1) * 2048) + wc * 32 + 8 * fq_;
; #pragma unroll
;     for (int n = 0; n < 2; ++n) { c1g[n] = *(const LAS f32x4*)(cl + 4 * n); c2g[n] = *(const LAS f32x4*)(cl + 256 + 4 * n); c1u[n] = *(const LAS f32x4*)(cl + 128 + 4 * n); c2u[n] = *(const LAS f32x4*)(cl + 256 + 128 + 4 * n); }
;     float ra[8], rb[8];
;     const LAS float* sl = (const LAS float*)(lds + 131072 + wid * 1024);
; #pragma unroll
;     for (int i = 0; i < 8; ++i) { typedef float f32x2_ __attribute__((ext_vector_type(2))); const f32x2_ sv = *(const LAS f32x2_*)(sl + (i >> 2) * 128 + ((i & 3) * 16 + fr_) * 2);
;       const float mu = sv.x * (1.0f / 1024.0f), var = fmaxf(sv.y * (1.0f / 1024.0f) - mu * mu, 0.f), rstd = rsqrtf(var + 1e-5f); ra[i] = rstd; rb[i] = -rstd * mu; }
; #pragma unroll
;     for (int ai = 0; ai < 2; ++ai)
; #pragma unroll
;       for (int m = 0; m < 4; ++m) {
;         const int row = u.pm * 256 + ai * 128 + wr * 64 + m * 16 + fr; const float a = ra[ai * 4 + m], bb = rb[ai * 4 + m];
;         u32x4 w;
; #pragma unroll
;         for (int n = 0; n < 2; ++n) {
;           const f32x4 gv = acc[ai][0][m][n] * a + c1g[n] * bb + c2g[n], uv = acc[ai][1][m][n] * a + c1u[n] * bb + c2u[n];
;           float h[4];
; #pragma unroll
;           for (int j = 0; j < 4; ++j) h[j] = gv[j] * sigmoidf_(gv[j]) * uv[j];
;           w[2 * n] = pkh2(h[0], h[1]); w[2 * n + 1] = pkh2(h[2], h[3]);
;         }
;         *(u32x4*)(H + (size_t)row * DFF + hcol) = w;
;         asm volatile("" ::: "memory");
;       }
;   }
.LBB0_212:
	v_mov_b32_e32 v130, v189
	v_mov_b32_e32 v204, v187
	s_add_i32 s15, s15, -1
	v_lshl_add_u32 v130, v130, 5, s13
	v_lshl_add_u32 v204, v204, 3, s30
	ds_read2_b64 v[206:209], v204 offset1:16
	ds_read_b128 v[154:157], v130
	ds_read_b128 v[158:161], v130 offset:1024
	ds_read_b128 v[150:153], v130 offset:512
	ds_read_b128 v[146:149], v130 offset:1536
	ds_read_b128 v[138:141], v130 offset:16
	ds_read_b128 v[142:145], v130 offset:1040
	ds_read_b128 v[134:137], v130 offset:528
	ds_read_b128 v[130:133], v130 offset:1552
	ds_read2_b64 v[210:213], v204 offset0:32 offset1:48
	s_mov_b32 s100, 0xbfb8aa3b
	s_mov_b32 s101, 1.0
	s_waitcnt lgkmcnt(0)
	v_pk_mul_f32 v[206:207], v[206:207], s[20:21] op_sel_hi:[1,0]
	s_nop 0
	v_fma_f32 v202, -v206, v206, v207
	v_max_f32_e32 v202, 0, v202
	v_add_f32_e32 v202, 0x3727c5ac, v202
	v_rsq_f32_e32 v190, v202
	s_nop 0
	v_mul_f32_e64 v192, v206, -v190
	v_pk_fma_f32 v[214:215], v[154:155], v[192:193], v[158:159] op_sel_hi:[1,0,1]
	v_pk_fma_f32 v[218:219], v[156:157], v[192:193], v[160:161] op_sel_hi:[1,0,1]
	v_pk_fma_f32 v[222:223], v[138:139], v[192:193], v[142:143] op_sel_hi:[1,0,1]
	v_pk_fma_f32 v[226:227], v[140:141], v[192:193], v[144:145] op_sel_hi:[1,0,1]
	v_pk_mul_f32 v[208:209], v[208:209], s[20:21] op_sel_hi:[1,0]
	v_pk_fma_f32 v[214:215], v[126:127], v[190:191], v[214:215] op_sel_hi:[1,0,1]
	v_pk_fma_f32 v[218:219], v[128:129], v[190:191], v[218:219] op_sel_hi:[1,0,1]
	v_pk_fma_f32 v[222:223], v[122:123], v[190:191], v[222:223] op_sel_hi:[1,0,1]
	v_pk_fma_f32 v[226:227], v[124:125], v[190:191], v[226:227] op_sel_hi:[1,0,1]
	v_fma_f32 v202, -v208, v208, v209
	v_pk_mul_f32 v[216:217], v[214:215], s[100:101] op_sel_hi:[1,0]
	v_pk_mul_f32 v[220:221], v[218:219], s[100:101] op_sel_hi:[1,0]
	v_pk_mul_f32 v[224:225], v[222:223], s[100:101] op_sel_hi:[1,0]
	v_pk_mul_f32 v[230:231], v[226:227], s[100:101] op_sel_hi:[1,0]
	v_max_f32_e32 v202, 0, v202
	v_exp_f32_e32 v216, v216
	v_exp_f32_e32 v217, v217
	v_exp_f32_e32 v220, v220
	v_exp_f32_e32 v221, v221
	v_exp_f32_e32 v224, v224
	v_exp_f32_e32 v225, v225
	v_exp_f32_e32 v230, v230
	v_exp_f32_e32 v231, v231
	v_add_f32_e32 v202, 0x3727c5ac, v202
	v_pk_add_f32 v[216:217], v[216:217], s[100:101] op_sel:[0,1] op_sel_hi:[1,1]
	v_pk_add_f32 v[220:221], v[220:221], s[100:101] op_sel:[0,1] op_sel_hi:[1,1]
	v_pk_add_f32 v[224:225], v[224:225], s[100:101] op_sel:[0,1] op_sel_hi:[1,1]
	v_pk_add_f32 v[230:231], v[230:231], s[100:101] op_sel:[0,1] op_sel_hi:[1,1]
	v_rsq_f32_e32 v186, v202
	v_rcp_f32_e32 v216, v216
	v_rcp_f32_e32 v217, v217
	v_rcp_f32_e32 v220, v220
	v_rcp_f32_e32 v221, v221
	v_rcp_f32_e32 v224, v224
	v_rcp_f32_e32 v225, v225
	v_rcp_f32_e32 v230, v230
	v_rcp_f32_e32 v231, v231
	v_mul_f32_e64 v188, v208, -v186
	v_pk_mul_f32 v[214:215], v[214:215], v[216:217]
	v_pk_mul_f32 v[218:219], v[218:219], v[220:221]
	v_pk_mul_f32 v[222:223], v[222:223], v[224:225]
	v_pk_mul_f32 v[226:227], v[226:227], v[230:231]
	v_pk_fma_f32 v[216:217], v[150:151], v[192:193], v[146:147] op_sel_hi:[1,0,1]
	v_pk_fma_f32 v[220:221], v[152:153], v[192:193], v[148:149] op_sel_hi:[1,0,1]
	v_pk_fma_f32 v[224:225], v[134:135], v[192:193], v[130:131] op_sel_hi:[1,0,1]
	v_pk_fma_f32 v[230:231], v[136:137], v[192:193], v[132:133] op_sel_hi:[1,0,1]
	v_pk_fma_f32 v[216:217], v[94:95], v[190:191], v[216:217] op_sel_hi:[1,0,1]
	v_pk_fma_f32 v[220:221], v[96:97], v[190:191], v[220:221] op_sel_hi:[1,0,1]
	v_pk_fma_f32 v[224:225], v[90:91], v[190:191], v[224:225] op_sel_hi:[1,0,1]
	v_pk_fma_f32 v[230:231], v[92:93], v[190:191], v[230:231] op_sel_hi:[1,0,1]
	v_pk_mul_f32 v[214:215], v[214:215], v[216:217]
	v_pk_mul_f32 v[218:219], v[218:219], v[220:221]
	v_pk_mul_f32 v[222:223], v[222:223], v[224:225]
	v_pk_mul_f32 v[226:227], v[226:227], v[230:231]
	v_cvt_pk_f16_f32 v244, v214, v215
	v_cvt_pk_f16_f32 v245, v218, v219
	v_cvt_pk_f16_f32 v246, v222, v223
	v_cvt_pk_f16_f32 v247, v226, v227
	global_store_dwordx4 v[170:171], v[244:247], off
	ds_read2_b64 v[206:209], v204 offset0:64 offset1:80
	v_pk_fma_f32 v[214:215], v[154:155], v[188:189], v[158:159] op_sel_hi:[1,0,1]
	v_pk_fma_f32 v[218:219], v[156:157], v[188:189], v[160:161] op_sel_hi:[1,0,1]
	v_pk_fma_f32 v[222:223], v[138:139], v[188:189], v[142:143] op_sel_hi:[1,0,1]
	v_pk_fma_f32 v[226:227], v[140:141], v[188:189], v[144:145] op_sel_hi:[1,0,1]
	v_pk_mul_f32 v[210:211], v[210:211], s[20:21] op_sel_hi:[1,0]
	v_pk_fma_f32 v[214:215], v[118:119], v[186:187], v[214:215] op_sel_hi:[1,0,1]
	v_pk_fma_f32 v[218:219], v[120:121], v[186:187], v[218:219] op_sel_hi:[1,0,1]
	v_pk_fma_f32 v[222:223], v[114:115], v[186:187], v[222:223] op_sel_hi:[1,0,1]
	v_pk_fma_f32 v[226:227], v[116:117], v[186:187], v[226:227] op_sel_hi:[1,0,1]
	v_fma_f32 v202, -v210, v210, v211
	v_pk_mul_f32 v[216:217], v[214:215], s[100:101] op_sel_hi:[1,0]
	v_pk_mul_f32 v[220:221], v[218:219], s[100:101] op_sel_hi:[1,0]
	v_pk_mul_f32 v[224:225], v[222:223], s[100:101] op_sel_hi:[1,0]
	v_pk_mul_f32 v[230:231], v[226:227], s[100:101] op_sel_hi:[1,0]
	v_max_f32_e32 v202, 0, v202
	v_exp_f32_e32 v216, v216
	v_exp_f32_e32 v217, v217
	v_exp_f32_e32 v220, v220
	v_exp_f32_e32 v221, v221
	v_exp_f32_e32 v224, v224
	v_exp_f32_e32 v225, v225
	v_exp_f32_e32 v230, v230
	v_exp_f32_e32 v231, v231
	v_add_f32_e32 v202, 0x3727c5ac, v202
	v_pk_add_f32 v[216:217], v[216:217], s[100:101] op_sel:[0,1] op_sel_hi:[1,1]
	v_pk_add_f32 v[220:221], v[220:221], s[100:101] op_sel:[0,1] op_sel_hi:[1,1]
	v_pk_add_f32 v[224:225], v[224:225], s[100:101] op_sel:[0,1] op_sel_hi:[1,1]
	v_pk_add_f32 v[230:231], v[230:231], s[100:101] op_sel:[0,1] op_sel_hi:[1,1]
	v_rsq_f32_e32 v190, v202
	v_rcp_f32_e32 v216, v216
	v_rcp_f32_e32 v217, v217
; #define LAS __attribute__((address_space(3)))
; DI unsigned pkh2(float a, float b) { typedef _Float16 h2 __attribute__((ext_vector_type(2))); h2 v; v[0] = (_Float16)a; v[1] = (_Float16)b; return __builtin_bit_cast(unsigned, v); }
; DI float sigmoidf_(float v) { return __builtin_amdgcn_rcpf(1.0f + __builtin_amdgcn_exp2f(-1.4426950408889634f * v)); }
;   DI void operator()(const f32x4 (&acc)[2][2][4][2], const pg8::Unit& u, int wr, int wc, int fr, int fq, LAS unsigned char* lds, int ui, int wid) const {
;     const int colg = u.pn * 256 + wc * 32 + 8 * fq, hcol = u.pn * 128 + wc * 32 + 8 * fq;
;     f32x4 c1g[2], c2g[2], c1u[2], c2u[2];
;     int fq_ = fq, fr_ = fr; asm volatile("" : "+v"(fq_), "+v"(fr_));
;     const LAS float* cl = (const LAS float*)(lds + 139264 + (ui & 1) * 2048) + wc * 32 + 8 * fq_;
; #pragma unroll
;     for (int n = 0; n < 2; ++n) { c1g[n] = *(const LAS f32x4*)(cl + 4 * n); c2g[n] = *(const LAS f32x4*)(cl + 256 + 4 * n); c1u[n] = *(const LAS f32x4*)(cl + 128 + 4 * n); c2u[n] = *(const LAS f32x4*)(cl + 256 + 128 + 4 * n); }
;     float ra[8], rb[8];
;     const LAS float* sl = (const LAS float*)(lds + 131072 + wid * 1024);
; #pragma unroll
;     for (int i = 0; i < 8; ++i) { typedef float f32x2_ __attribute__((ext_vector_type(2))); const f32x2_ sv = *(const LAS f32x2_*)(sl + (i >> 2) * 128 + ((i & 3) * 16 + fr_) * 2);
;       const float mu = sv.x * (1.0f / 1024.0f), var = fmaxf(sv.y * (1.0f / 1024.0f) - mu * mu, 0.f), rstd = rsqrtf(var + 1e-5f); ra[i] = rstd; rb[i] = -rstd * mu; }
; #pragma unroll
;     for (int ai = 0; ai < 2; ++ai)
; #pragma unroll
;       for (int m = 0; m < 4; ++m) {
;         const int row = u.pm * 256 + ai * 128 + wr * 64 + m * 16 + fr; const float a = ra[ai * 4 + m], bb = rb[ai * 4 + m];
;         u32x4 w;
; #pragma unroll
;         for (int n = 0; n < 2; ++n) {
;           const f32x4 gv = acc[ai][0][m][n] * a + c1g[n] * bb + c2g[n], uv = acc[ai][1][m][n] * a + c1u[n] * bb + c2u[n];
;           float h[4];
; #pragma unroll
;           for (int j = 0; j < 4; ++j) h[j] = gv[j] * sigmoidf_(gv[j]) * uv[j];
;           w[2 * n] = pkh2(h[0], h[1]); w[2 * n + 1] = pkh2(h[2], h[3]);
;         }
;         *(u32x4*)(H + (size_t)row * DFF + hcol) = w;
;         asm volatile("" ::: "memory");
;       }
;   }
	v_rcp_f32_e32 v220, v220
	v_rcp_f32_e32 v221, v221
	v_rcp_f32_e32 v224, v224
	v_rcp_f32_e32 v225, v225
	v_rcp_f32_e32 v230, v230
	v_rcp_f32_e32 v231, v231
	v_mul_f32_e64 v192, v210, -v190
	v_pk_mul_f32 v[214:215], v[214:215], v[216:217]
	v_pk_mul_f32 v[218:219], v[218:219], v[220:221]
	v_pk_mul_f32 v[222:223], v[222:223], v[224:225]
	v_pk_mul_f32 v[226:227], v[226:227], v[230:231]
	v_pk_fma_f32 v[216:217], v[150:151], v[188:189], v[146:147] op_sel_hi:[1,0,1]
	v_pk_fma_f32 v[220:221], v[152:153], v[188:189], v[148:149] op_sel_hi:[1,0,1]
	v_pk_fma_f32 v[224:225], v[134:135], v[188:189], v[130:131] op_sel_hi:[1,0,1]
	v_pk_fma_f32 v[230:231], v[136:137], v[188:189], v[132:133] op_sel_hi:[1,0,1]
	v_pk_fma_f32 v[216:217], v[86:87], v[186:187], v[216:217] op_sel_hi:[1,0,1]
	v_pk_fma_f32 v[220:221], v[88:89], v[186:187], v[220:221] op_sel_hi:[1,0,1]
	v_pk_fma_f32 v[224:225], v[82:83], v[186:187], v[224:225] op_sel_hi:[1,0,1]
	v_pk_fma_f32 v[230:231], v[84:85], v[186:187], v[230:231] op_sel_hi:[1,0,1]
	v_pk_mul_f32 v[214:215], v[214:215], v[216:217]
	v_pk_mul_f32 v[218:219], v[218:219], v[220:221]
	v_pk_mul_f32 v[222:223], v[222:223], v[224:225]
	v_pk_mul_f32 v[226:227], v[226:227], v[230:231]
	v_cvt_pk_f16_f32 v244, v214, v215
	v_cvt_pk_f16_f32 v245, v218, v219
	v_cvt_pk_f16_f32 v246, v222, v223
	v_cvt_pk_f16_f32 v247, v226, v227
	global_store_dwordx4 v[172:173], v[244:247], off
	v_pk_fma_f32 v[214:215], v[154:155], v[192:193], v[158:159] op_sel_hi:[1,0,1]
	v_pk_fma_f32 v[218:219], v[156:157], v[192:193], v[160:161] op_sel_hi:[1,0,1]
	v_pk_fma_f32 v[222:223], v[138:139], v[192:193], v[142:143] op_sel_hi:[1,0,1]
	v_pk_fma_f32 v[226:227], v[140:141], v[192:193], v[144:145] op_sel_hi:[1,0,1]
	v_pk_mul_f32 v[212:213], v[212:213], s[20:21] op_sel_hi:[1,0]
	v_pk_fma_f32 v[214:215], v[110:111], v[190:191], v[214:215] op_sel_hi:[1,0,1]
	v_pk_fma_f32 v[218:219], v[112:113], v[190:191], v[218:219] op_sel_hi:[1,0,1]
	v_pk_fma_f32 v[222:223], v[106:107], v[190:191], v[222:223] op_sel_hi:[1,0,1]
	v_pk_fma_f32 v[226:227], v[108:109], v[190:191], v[226:227] op_sel_hi:[1,0,1]
	v_fma_f32 v202, -v212, v212, v213
	v_pk_mul_f32 v[216:217], v[214:215], s[100:101] op_sel_hi:[1,0]
	v_pk_mul_f32 v[220:221], v[218:219], s[100:101] op_sel_hi:[1,0]
	v_pk_mul_f32 v[224:225], v[222:223], s[100:101] op_sel_hi:[1,0]
	v_pk_mul_f32 v[230:231], v[226:227], s[100:101] op_sel_hi:[1,0]
	v_max_f32_e32 v202, 0, v202
	v_exp_f32_e32 v216, v216
	v_exp_f32_e32 v217, v217
	v_exp_f32_e32 v220, v220
	v_exp_f32_e32 v221, v221
	v_exp_f32_e32 v224, v224
	v_exp_f32_e32 v225, v225
	v_exp_f32_e32 v230, v230
	v_exp_f32_e32 v231, v231
	v_add_f32_e32 v202, 0x3727c5ac, v202
	v_pk_add_f32 v[216:217], v[216:217], s[100:101] op_sel:[0,1] op_sel_hi:[1,1]
	v_pk_add_f32 v[220:221], v[220:221], s[100:101] op_sel:[0,1] op_sel_hi:[1,1]
	v_pk_add_f32 v[224:225], v[224:225], s[100:101] op_sel:[0,1] op_sel_hi:[1,1]
	v_pk_add_f32 v[230:231], v[230:231], s[100:101] op_sel:[0,1] op_sel_hi:[1,1]
	v_rsq_f32_e32 v186, v202
	v_rcp_f32_e32 v216, v216
	v_rcp_f32_e32 v217, v217
	v_rcp_f32_e32 v220, v220
	v_rcp_f32_e32 v221, v221
	v_rcp_f32_e32 v224, v224
	v_rcp_f32_e32 v225, v225
	v_rcp_f32_e32 v230, v230
	v_rcp_f32_e32 v231, v231
	v_mul_f32_e64 v188, v212, -v186
	v_pk_mul_f32 v[214:215], v[214:215], v[216:217]
	v_pk_mul_f32 v[218:219], v[218:219], v[220:221]
	v_pk_mul_f32 v[222:223], v[222:223], v[224:225]
	v_pk_mul_f32 v[226:227], v[226:227], v[230:231]
	v_pk_fma_f32 v[216:217], v[150:151], v[192:193], v[146:147] op_sel_hi:[1,0,1]
	v_pk_fma_f32 v[220:221], v[152:153], v[192:193], v[148:149] op_sel_hi:[1,0,1]
	v_pk_fma_f32 v[224:225], v[134:135], v[192:193], v[130:131] op_sel_hi:[1,0,1]
	v_pk_fma_f32 v[230:231], v[136:137], v[192:193], v[132:133] op_sel_hi:[1,0,1]
	v_pk_fma_f32 v[216:217], v[78:79], v[190:191], v[216:217] op_sel_hi:[1,0,1]
	v_pk_fma_f32 v[220:221], v[80:81], v[190:191], v[220:221] op_sel_hi:[1,0,1]
	v_pk_fma_f32 v[224:225], v[74:75], v[190:191], v[224:225] op_sel_hi:[1,0,1]
	v_pk_fma_f32 v[230:231], v[76:77], v[190:191], v[230:231] op_sel_hi:[1,0,1]
	v_pk_mul_f32 v[214:215], v[214:215], v[216:217]
	v_pk_mul_f32 v[218:219], v[218:219], v[220:221]
	v_pk_mul_f32 v[222:223], v[222:223], v[224:225]
	v_pk_mul_f32 v[226:227], v[226:227], v[230:231]
	v_cvt_pk_f16_f32 v244, v214, v215
	v_cvt_pk_f16_f32 v245, v218, v219
	v_cvt_pk_f16_f32 v246, v222, v223
	v_cvt_pk_f16_f32 v247, v226, v227
	global_store_dwordx4 v[174:175], v[244:247], off
	ds_read2_b64 v[210:213], v204 offset0:96 offset1:112
	v_pk_fma_f32 v[214:215], v[154:155], v[188:189], v[158:159] op_sel_hi:[1,0,1]
	v_pk_fma_f32 v[218:219], v[156:157], v[188:189], v[160:161] op_sel_hi:[1,0,1]
	v_pk_fma_f32 v[222:223], v[138:139], v[188:189], v[142:143] op_sel_hi:[1,0,1]
	v_pk_fma_f32 v[226:227], v[140:141], v[188:189], v[144:145] op_sel_hi:[1,0,1]
	s_waitcnt lgkmcnt(0)
; #define LAS __attribute__((address_space(3)))
; DI unsigned pkh2(float a, float b) { typedef _Float16 h2 __attribute__((ext_vector_type(2))); h2 v; v[0] = (_Float16)a; v[1] = (_Float16)b; return __builtin_bit_cast(unsigned, v); }
; DI float sigmoidf_(float v) { return __builtin_amdgcn_rcpf(1.0f + __builtin_amdgcn_exp2f(-1.4426950408889634f * v)); }
;   DI void operator()(const f32x4 (&acc)[2][2][4][2], const pg8::Unit& u, int wr, int wc, int fr, int fq, LAS unsigned char* lds, int ui, int wid) const {
;     const int colg = u.pn * 256 + wc * 32 + 8 * fq, hcol = u.pn * 128 + wc * 32 + 8 * fq;
;     f32x4 c1g[2], c2g[2], c1u[2], c2u[2];
;     int fq_ = fq, fr_ = fr; asm volatile("" : "+v"(fq_), "+v"(fr_));
;     const LAS float* cl = (const LAS float*)(lds + 139264 + (ui & 1) * 2048) + wc * 32 + 8 * fq_;
; #pragma unroll
;     for (int n = 0; n < 2; ++n) { c1g[n] = *(const LAS f32x4*)(cl + 4 * n); c2g[n] = *(const LAS f32x4*)(cl + 256 + 4 * n); c1u[n] = *(const LAS f32x4*)(cl + 128 + 4 * n); c2u[n] = *(const LAS f32x4*)(cl + 256 + 128 + 4 * n); }
;     float ra[8], rb[8];
;     const LAS float* sl = (const LAS float*)(lds + 131072 + wid * 1024);
; #pragma unroll
;     for (int i = 0; i < 8; ++i) { typedef float f32x2_ __attribute__((ext_vector_type(2))); const f32x2_ sv = *(const LAS f32x2_*)(sl + (i >> 2) * 128 + ((i & 3) * 16 + fr_) * 2);
;       const float mu = sv.x * (1.0f / 1024.0f), var = fmaxf(sv.y * (1.0f / 1024.0f) - mu * mu, 0.f), rstd = rsqrtf(var + 1e-5f); ra[i] = rstd; rb[i] = -rstd * mu; }
; #pragma unroll
;     for (int ai = 0; ai < 2; ++ai)
; #pragma unroll
;       for (int m = 0; m < 4; ++m) {
;         const int row = u.pm * 256 + ai * 128 + wr * 64 + m * 16 + fr; const float a = ra[ai * 4 + m], bb = rb[ai * 4 + m];
;         u32x4 w;
; #pragma unroll
;         for (int n = 0; n < 2; ++n) {
;           const f32x4 gv = acc[ai][0][m][n] * a + c1g[n] * bb + c2g[n], uv = acc[ai][1][m][n] * a + c1u[n] * bb + c2u[n];
;           float h[4];
; #pragma unroll
;           for (int j = 0; j < 4; ++j) h[j] = gv[j] * sigmoidf_(gv[j]) * uv[j];
;           w[2 * n] = pkh2(h[0], h[1]); w[2 * n + 1] = pkh2(h[2], h[3]);
;         }
;         *(u32x4*)(H + (size_t)row * DFF + hcol) = w;
;         asm volatile("" ::: "memory");
;       }
;   }
	v_pk_mul_f32 v[206:207], v[206:207], s[20:21] op_sel_hi:[1,0]
	v_pk_fma_f32 v[214:215], v[102:103], v[186:187], v[214:215] op_sel_hi:[1,0,1]
	v_pk_fma_f32 v[218:219], v[104:105], v[186:187], v[218:219] op_sel_hi:[1,0,1]
	v_pk_fma_f32 v[222:223], v[98:99], v[186:187], v[222:223] op_sel_hi:[1,0,1]
	v_pk_fma_f32 v[226:227], v[100:101], v[186:187], v[226:227] op_sel_hi:[1,0,1]
	v_fma_f32 v202, -v206, v206, v207
	v_pk_mul_f32 v[216:217], v[214:215], s[100:101] op_sel_hi:[1,0]
	v_pk_mul_f32 v[220:221], v[218:219], s[100:101] op_sel_hi:[1,0]
	v_pk_mul_f32 v[224:225], v[222:223], s[100:101] op_sel_hi:[1,0]
	v_pk_mul_f32 v[230:231], v[226:227], s[100:101] op_sel_hi:[1,0]
	v_max_f32_e32 v202, 0, v202
	v_exp_f32_e32 v216, v216
	v_exp_f32_e32 v217, v217
	v_exp_f32_e32 v220, v220
	v_exp_f32_e32 v221, v221
	v_exp_f32_e32 v224, v224
	v_exp_f32_e32 v225, v225
	v_exp_f32_e32 v230, v230
	v_exp_f32_e32 v231, v231
	v_add_f32_e32 v202, 0x3727c5ac, v202
	v_pk_add_f32 v[216:217], v[216:217], s[100:101] op_sel:[0,1] op_sel_hi:[1,1]
	v_pk_add_f32 v[220:221], v[220:221], s[100:101] op_sel:[0,1] op_sel_hi:[1,1]
	v_pk_add_f32 v[224:225], v[224:225], s[100:101] op_sel:[0,1] op_sel_hi:[1,1]
	v_pk_add_f32 v[230:231], v[230:231], s[100:101] op_sel:[0,1] op_sel_hi:[1,1]
	v_rsq_f32_e32 v190, v202
	v_rcp_f32_e32 v216, v216
	v_rcp_f32_e32 v217, v217
	v_rcp_f32_e32 v220, v220
	v_rcp_f32_e32 v221, v221
	v_rcp_f32_e32 v224, v224
	v_rcp_f32_e32 v225, v225
	v_rcp_f32_e32 v230, v230
	v_rcp_f32_e32 v231, v231
	v_mul_f32_e64 v192, v206, -v190
	v_pk_mul_f32 v[214:215], v[214:215], v[216:217]
	v_pk_mul_f32 v[218:219], v[218:219], v[220:221]
	v_pk_mul_f32 v[222:223], v[222:223], v[224:225]
	v_pk_mul_f32 v[226:227], v[226:227], v[230:231]
	v_pk_fma_f32 v[216:217], v[150:151], v[188:189], v[146:147] op_sel_hi:[1,0,1]
	v_pk_fma_f32 v[220:221], v[152:153], v[188:189], v[148:149] op_sel_hi:[1,0,1]
	v_pk_fma_f32 v[224:225], v[134:135], v[188:189], v[130:131] op_sel_hi:[1,0,1]
	v_pk_fma_f32 v[230:231], v[136:137], v[188:189], v[132:133] op_sel_hi:[1,0,1]
	v_pk_fma_f32 v[216:217], v[70:71], v[186:187], v[216:217] op_sel_hi:[1,0,1]
	v_pk_fma_f32 v[220:221], v[72:73], v[186:187], v[220:221] op_sel_hi:[1,0,1]
	v_pk_fma_f32 v[224:225], v[66:67], v[186:187], v[224:225] op_sel_hi:[1,0,1]
	v_pk_fma_f32 v[230:231], v[68:69], v[186:187], v[230:231] op_sel_hi:[1,0,1]
	v_pk_mul_f32 v[214:215], v[214:215], v[216:217]
	v_pk_mul_f32 v[218:219], v[218:219], v[220:221]
	v_pk_mul_f32 v[222:223], v[222:223], v[224:225]
	v_pk_mul_f32 v[226:227], v[226:227], v[230:231]
	v_cvt_pk_f16_f32 v244, v214, v215
	v_cvt_pk_f16_f32 v245, v218, v219
	v_cvt_pk_f16_f32 v246, v222, v223
	v_cvt_pk_f16_f32 v247, v226, v227
	global_store_dwordx4 v[176:177], v[244:247], off
	v_pk_fma_f32 v[214:215], v[154:155], v[192:193], v[158:159] op_sel_hi:[1,0,1]
	v_pk_fma_f32 v[218:219], v[156:157], v[192:193], v[160:161] op_sel_hi:[1,0,1]
	v_pk_fma_f32 v[222:223], v[138:139], v[192:193], v[142:143] op_sel_hi:[1,0,1]
	v_pk_fma_f32 v[226:227], v[140:141], v[192:193], v[144:145] op_sel_hi:[1,0,1]
	v_pk_mul_f32 v[208:209], v[208:209], s[20:21] op_sel_hi:[1,0]
	v_pk_fma_f32 v[214:215], v[62:63], v[190:191], v[214:215] op_sel_hi:[1,0,1]
	v_pk_fma_f32 v[218:219], v[64:65], v[190:191], v[218:219] op_sel_hi:[1,0,1]
	v_pk_fma_f32 v[222:223], v[58:59], v[190:191], v[222:223] op_sel_hi:[1,0,1]
	v_pk_fma_f32 v[226:227], v[60:61], v[190:191], v[226:227] op_sel_hi:[1,0,1]
	v_fma_f32 v202, -v208, v208, v209
	v_pk_mul_f32 v[216:217], v[214:215], s[100:101] op_sel_hi:[1,0]
	v_pk_mul_f32 v[220:221], v[218:219], s[100:101] op_sel_hi:[1,0]
	v_pk_mul_f32 v[224:225], v[222:223], s[100:101] op_sel_hi:[1,0]
	v_pk_mul_f32 v[230:231], v[226:227], s[100:101] op_sel_hi:[1,0]
	v_max_f32_e32 v202, 0, v202
	v_exp_f32_e32 v216, v216
	v_exp_f32_e32 v217, v217
	v_exp_f32_e32 v220, v220
	v_exp_f32_e32 v221, v221
	v_exp_f32_e32 v224, v224
	v_exp_f32_e32 v225, v225
	v_exp_f32_e32 v230, v230
	v_exp_f32_e32 v231, v231
	v_add_f32_e32 v202, 0x3727c5ac, v202
	v_pk_add_f32 v[216:217], v[216:217], s[100:101] op_sel:[0,1] op_sel_hi:[1,1]
	v_pk_add_f32 v[220:221], v[220:221], s[100:101] op_sel:[0,1] op_sel_hi:[1,1]
	v_pk_add_f32 v[224:225], v[224:225], s[100:101] op_sel:[0,1] op_sel_hi:[1,1]
	v_pk_add_f32 v[230:231], v[230:231], s[100:101] op_sel:[0,1] op_sel_hi:[1,1]
	v_rsq_f32_e32 v186, v202
	v_rcp_f32_e32 v216, v216
	v_rcp_f32_e32 v217, v217
	v_rcp_f32_e32 v220, v220
	v_rcp_f32_e32 v221, v221
	v_rcp_f32_e32 v224, v224
	v_rcp_f32_e32 v225, v225
	v_rcp_f32_e32 v230, v230
	v_rcp_f32_e32 v231, v231
	v_mul_f32_e64 v188, v208, -v186
	v_pk_mul_f32 v[214:215], v[214:215], v[216:217]
	v_pk_mul_f32 v[218:219], v[218:219], v[220:221]
	v_pk_mul_f32 v[222:223], v[222:223], v[224:225]
	v_pk_mul_f32 v[226:227], v[226:227], v[230:231]
	v_pk_fma_f32 v[216:217], v[150:151], v[192:193], v[146:147] op_sel_hi:[1,0,1]
	v_pk_fma_f32 v[220:221], v[152:153], v[192:193], v[148:149] op_sel_hi:[1,0,1]
	v_pk_fma_f32 v[224:225], v[134:135], v[192:193], v[130:131] op_sel_hi:[1,0,1]
	v_pk_fma_f32 v[230:231], v[136:137], v[192:193], v[132:133] op_sel_hi:[1,0,1]
	v_pk_fma_f32 v[216:217], v[28:29], v[190:191], v[216:217] op_sel_hi:[1,0,1]
	v_pk_fma_f32 v[220:221], v[30:31], v[190:191], v[220:221] op_sel_hi:[1,0,1]
	v_pk_fma_f32 v[224:225], v[24:25], v[190:191], v[224:225] op_sel_hi:[1,0,1]
	v_pk_fma_f32 v[230:231], v[26:27], v[190:191], v[230:231] op_sel_hi:[1,0,1]
	v_pk_mul_f32 v[214:215], v[214:215], v[216:217]
	v_pk_mul_f32 v[218:219], v[218:219], v[220:221]
	v_pk_mul_f32 v[222:223], v[222:223], v[224:225]
	v_pk_mul_f32 v[226:227], v[226:227], v[230:231]
	v_cvt_pk_f16_f32 v244, v214, v215
	v_cvt_pk_f16_f32 v245, v218, v219
	v_cvt_pk_f16_f32 v246, v222, v223
	v_cvt_pk_f16_f32 v247, v226, v227
	global_store_dwordx4 v[178:179], v[244:247], off
	v_pk_fma_f32 v[214:215], v[154:155], v[188:189], v[158:159] op_sel_hi:[1,0,1]
	v_pk_fma_f32 v[218:219], v[156:157], v[188:189], v[160:161] op_sel_hi:[1,0,1]
	v_pk_fma_f32 v[222:223], v[138:139], v[188:189], v[142:143] op_sel_hi:[1,0,1]
	v_pk_fma_f32 v[226:227], v[140:141], v[188:189], v[144:145] op_sel_hi:[1,0,1]
	s_waitcnt lgkmcnt(0)
; #define LAS __attribute__((address_space(3)))
; DI unsigned pkh2(float a, float b) { typedef _Float16 h2 __attribute__((ext_vector_type(2))); h2 v; v[0] = (_Float16)a; v[1] = (_Float16)b; return __builtin_bit_cast(unsigned, v); }
; DI float sigmoidf_(float v) { return __builtin_amdgcn_rcpf(1.0f + __builtin_amdgcn_exp2f(-1.4426950408889634f * v)); }
;   DI void operator()(const f32x4 (&acc)[2][2][4][2], const pg8::Unit& u, int wr, int wc, int fr, int fq, LAS unsigned char* lds, int ui, int wid) const {
;     const int colg = u.pn * 256 + wc * 32 + 8 * fq, hcol = u.pn * 128 + wc * 32 + 8 * fq;
;     f32x4 c1g[2], c2g[2], c1u[2], c2u[2];
;     int fq_ = fq, fr_ = fr; asm volatile("" : "+v"(fq_), "+v"(fr_));
;     const LAS float* cl = (const LAS float*)(lds + 139264 + (ui & 1) * 2048) + wc * 32 + 8 * fq_;
; #pragma unroll
;     for (int n = 0; n < 2; ++n) { c1g[n] = *(const LAS f32x4*)(cl + 4 * n); c2g[n] = *(const LAS f32x4*)(cl + 256 + 4 * n); c1u[n] = *(const LAS f32x4*)(cl + 128 + 4 * n); c2u[n] = *(const LAS f32x4*)(cl + 256 + 128 + 4 * n); }
;     float ra[8], rb[8];
;     const LAS float* sl = (const LAS float*)(lds + 131072 + wid * 1024);
; #pragma unroll
;     for (int i = 0; i < 8; ++i) { typedef float f32x2_ __attribute__((ext_vector_type(2))); const f32x2_ sv = *(const LAS f32x2_*)(sl + (i >> 2) * 128 + ((i & 3) * 16 + fr_) * 2);
;       const float mu = sv.x * (1.0f / 1024.0f), var = fmaxf(sv.y * (1.0f / 1024.0f) - mu * mu, 0.f), rstd = rsqrtf(var + 1e-5f); ra[i] = rstd; rb[i] = -rstd * mu; }
; #pragma unroll
;     for (int ai = 0; ai < 2; ++ai)
; #pragma unroll
;       for (int m = 0; m < 4; ++m) {
;         const int row = u.pm * 256 + ai * 128 + wr * 64 + m * 16 + fr; const float a = ra[ai * 4 + m], bb = rb[ai * 4 + m];
;         u32x4 w;
; #pragma unroll
;         for (int n = 0; n < 2; ++n) {
;           const f32x4 gv = acc[ai][0][m][n] * a + c1g[n] * bb + c2g[n], uv = acc[ai][1][m][n] * a + c1u[n] * bb + c2u[n];
;           float h[4];
; #pragma unroll
;           for (int j = 0; j < 4; ++j) h[j] = gv[j] * sigmoidf_(gv[j]) * uv[j];
;           w[2 * n] = pkh2(h[0], h[1]); w[2 * n + 1] = pkh2(h[2], h[3]);
;         }
;         *(u32x4*)(H + (size_t)row * DFF + hcol) = w;
;         asm volatile("" ::: "memory");
;       }
;   }
	v_pk_mul_f32 v[210:211], v[210:211], s[20:21] op_sel_hi:[1,0]
	v_pk_fma_f32 v[214:215], v[54:55], v[186:187], v[214:215] op_sel_hi:[1,0,1]
	v_pk_fma_f32 v[218:219], v[56:57], v[186:187], v[218:219] op_sel_hi:[1,0,1]
	v_pk_fma_f32 v[222:223], v[50:51], v[186:187], v[222:223] op_sel_hi:[1,0,1]
	v_pk_fma_f32 v[226:227], v[52:53], v[186:187], v[226:227] op_sel_hi:[1,0,1]
	v_fma_f32 v202, -v210, v210, v211
	v_pk_mul_f32 v[216:217], v[214:215], s[100:101] op_sel_hi:[1,0]
	v_pk_mul_f32 v[220:221], v[218:219], s[100:101] op_sel_hi:[1,0]
	v_pk_mul_f32 v[224:225], v[222:223], s[100:101] op_sel_hi:[1,0]
	v_pk_mul_f32 v[230:231], v[226:227], s[100:101] op_sel_hi:[1,0]
	v_max_f32_e32 v202, 0, v202
	v_exp_f32_e32 v216, v216
	v_exp_f32_e32 v217, v217
	v_exp_f32_e32 v220, v220
	v_exp_f32_e32 v221, v221
	v_exp_f32_e32 v224, v224
	v_exp_f32_e32 v225, v225
	v_exp_f32_e32 v230, v230
	v_exp_f32_e32 v231, v231
	v_add_f32_e32 v202, 0x3727c5ac, v202
	v_pk_add_f32 v[216:217], v[216:217], s[100:101] op_sel:[0,1] op_sel_hi:[1,1]
	v_pk_add_f32 v[220:221], v[220:221], s[100:101] op_sel:[0,1] op_sel_hi:[1,1]
	v_pk_add_f32 v[224:225], v[224:225], s[100:101] op_sel:[0,1] op_sel_hi:[1,1]
	v_pk_add_f32 v[230:231], v[230:231], s[100:101] op_sel:[0,1] op_sel_hi:[1,1]
	v_rsq_f32_e32 v190, v202
	v_rcp_f32_e32 v216, v216
	v_rcp_f32_e32 v217, v217
	v_rcp_f32_e32 v220, v220
	v_rcp_f32_e32 v221, v221
	v_rcp_f32_e32 v224, v224
	v_rcp_f32_e32 v225, v225
	v_rcp_f32_e32 v230, v230
	v_rcp_f32_e32 v231, v231
	v_mul_f32_e64 v192, v210, -v190
	v_pk_mul_f32 v[214:215], v[214:215], v[216:217]
	v_pk_mul_f32 v[218:219], v[218:219], v[220:221]
	v_pk_mul_f32 v[222:223], v[222:223], v[224:225]
	v_pk_mul_f32 v[226:227], v[226:227], v[230:231]
	v_pk_fma_f32 v[216:217], v[150:151], v[188:189], v[146:147] op_sel_hi:[1,0,1]
	v_pk_fma_f32 v[220:221], v[152:153], v[188:189], v[148:149] op_sel_hi:[1,0,1]
	v_pk_fma_f32 v[224:225], v[134:135], v[188:189], v[130:131] op_sel_hi:[1,0,1]
	v_pk_fma_f32 v[230:231], v[136:137], v[188:189], v[132:133] op_sel_hi:[1,0,1]
	v_pk_fma_f32 v[216:217], v[20:21], v[186:187], v[216:217] op_sel_hi:[1,0,1]
	v_pk_fma_f32 v[220:221], v[22:23], v[186:187], v[220:221] op_sel_hi:[1,0,1]
	v_pk_fma_f32 v[224:225], v[16:17], v[186:187], v[224:225] op_sel_hi:[1,0,1]
	v_pk_fma_f32 v[230:231], v[18:19], v[186:187], v[230:231] op_sel_hi:[1,0,1]
	v_pk_mul_f32 v[214:215], v[214:215], v[216:217]
	v_pk_mul_f32 v[218:219], v[218:219], v[220:221]
	v_pk_mul_f32 v[222:223], v[222:223], v[224:225]
	v_pk_mul_f32 v[226:227], v[226:227], v[230:231]
	v_cvt_pk_f16_f32 v244, v214, v215
	v_cvt_pk_f16_f32 v245, v218, v219
	v_cvt_pk_f16_f32 v246, v222, v223
	v_cvt_pk_f16_f32 v247, v226, v227
	global_store_dwordx4 v[180:181], v[244:247], off
	v_pk_fma_f32 v[214:215], v[154:155], v[192:193], v[158:159] op_sel_hi:[1,0,1]
	v_pk_fma_f32 v[218:219], v[156:157], v[192:193], v[160:161] op_sel_hi:[1,0,1]
	v_pk_fma_f32 v[222:223], v[138:139], v[192:193], v[142:143] op_sel_hi:[1,0,1]
	v_pk_fma_f32 v[226:227], v[140:141], v[192:193], v[144:145] op_sel_hi:[1,0,1]
	v_pk_mul_f32 v[212:213], v[212:213], s[20:21] op_sel_hi:[1,0]
	v_pk_fma_f32 v[214:215], v[46:47], v[190:191], v[214:215] op_sel_hi:[1,0,1]
	v_pk_fma_f32 v[218:219], v[48:49], v[190:191], v[218:219] op_sel_hi:[1,0,1]
	v_pk_fma_f32 v[222:223], v[42:43], v[190:191], v[222:223] op_sel_hi:[1,0,1]
	v_pk_fma_f32 v[226:227], v[44:45], v[190:191], v[226:227] op_sel_hi:[1,0,1]
	v_fma_f32 v202, -v212, v212, v213
	v_pk_mul_f32 v[216:217], v[214:215], s[100:101] op_sel_hi:[1,0]
	v_pk_mul_f32 v[220:221], v[218:219], s[100:101] op_sel_hi:[1,0]
	v_pk_mul_f32 v[224:225], v[222:223], s[100:101] op_sel_hi:[1,0]
	v_pk_mul_f32 v[230:231], v[226:227], s[100:101] op_sel_hi:[1,0]
	v_max_f32_e32 v202, 0, v202
	v_exp_f32_e32 v216, v216
	v_exp_f32_e32 v217, v217
	v_exp_f32_e32 v220, v220
	v_exp_f32_e32 v221, v221
	v_exp_f32_e32 v224, v224
	v_exp_f32_e32 v225, v225
	v_exp_f32_e32 v230, v230
	v_exp_f32_e32 v231, v231
	v_add_f32_e32 v202, 0x3727c5ac, v202
	v_pk_add_f32 v[216:217], v[216:217], s[100:101] op_sel:[0,1] op_sel_hi:[1,1]
	v_pk_add_f32 v[220:221], v[220:221], s[100:101] op_sel:[0,1] op_sel_hi:[1,1]
	v_pk_add_f32 v[224:225], v[224:225], s[100:101] op_sel:[0,1] op_sel_hi:[1,1]
	v_pk_add_f32 v[230:231], v[230:231], s[100:101] op_sel:[0,1] op_sel_hi:[1,1]
	v_rsq_f32_e32 v186, v202
; #define LAS __attribute__((address_space(3)))
; DI unsigned pkh2(float a, float b) { typedef _Float16 h2 __attribute__((ext_vector_type(2))); h2 v; v[0] = (_Float16)a; v[1] = (_Float16)b; return __builtin_bit_cast(unsigned, v); }
; template <class Epi>
; DI void gemm_phase(int wv, LAS unsigned char* lds, const Gemm g, const StaticOrder& S, const Epi& E) {
;     ...
;     for (int r_ = 0; r_ < E.reps; ++r_) E(acc, cur, wr, wc, fr, fq, lds, ui, wid);
;   DI void operator()(const f32x4 (&acc)[2][2][4][2], const pg8::Unit& u, int wr, int wc, int fr, int fq, LAS unsigned char* lds, int ui, int wid) const {
;     const int colg = u.pn * 256 + wc * 32 + 8 * fq, hcol = u.pn * 128 + wc * 32 + 8 * fq;
;     f32x4 c1g[2], c2g[2], c1u[2], c2u[2];
;     int fq_ = fq, fr_ = fr; asm volatile("" : "+v"(fq_), "+v"(fr_));
;     const LAS float* cl = (const LAS float*)(lds + 139264 + (ui & 1) * 2048) + wc * 32 + 8 * fq_;
; #pragma unroll
;     for (int n = 0; n < 2; ++n) { c1g[n] = *(const LAS f32x4*)(cl + 4 * n); c2g[n] = *(const LAS f32x4*)(cl + 256 + 4 * n); c1u[n] = *(const LAS f32x4*)(cl + 128 + 4 * n); c2u[n] = *(const LAS f32x4*)(cl + 256 + 128 + 4 * n); }
;     float ra[8], rb[8];
;     const LAS float* sl = (const LAS float*)(lds + 131072 + wid * 1024);
; #pragma unroll
;     for (int i = 0; i < 8; ++i) { typedef float f32x2_ __attribute__((ext_vector_type(2))); const f32x2_ sv = *(const LAS f32x2_*)(sl + (i >> 2) * 128 + ((i & 3) * 16 + fr_) * 2);
;       const float mu = sv.x * (1.0f / 1024.0f), var = fmaxf(sv.y * (1.0f / 1024.0f) - mu * mu, 0.f), rstd = rsqrtf(var + 1e-5f); ra[i] = rstd; rb[i] = -rstd * mu; }
; #pragma unroll
;     for (int ai = 0; ai < 2; ++ai)
; #pragma unroll
;       for (int m = 0; m < 4; ++m) {
;         const int row = u.pm * 256 + ai * 128 + wr * 64 + m * 16 + fr; const float a = ra[ai * 4 + m], bb = rb[ai * 4 + m];
;         u32x4 w;
; #pragma unroll
;         for (int n = 0; n < 2; ++n) {
;           const f32x4 gv = acc[ai][0][m][n] * a + c1g[n] * bb + c2g[n], uv = acc[ai][1][m][n] * a + c1u[n] * bb + c2u[n];
;           float h[4];
; #pragma unroll
;           for (int j = 0; j < 4; ++j) h[j] = gv[j] * sigmoidf_(gv[j]) * uv[j];
;           w[2 * n] = pkh2(h[0], h[1]); w[2 * n + 1] = pkh2(h[2], h[3]);
;         }
;         *(u32x4*)(H + (size_t)row * DFF + hcol) = w;
;         asm volatile("" ::: "memory");
;       }
;   }
	v_rcp_f32_e32 v216, v216
	v_rcp_f32_e32 v217, v217
	v_rcp_f32_e32 v220, v220
	v_rcp_f32_e32 v221, v221
	v_rcp_f32_e32 v224, v224
	v_rcp_f32_e32 v225, v225
	v_rcp_f32_e32 v230, v230
	v_rcp_f32_e32 v231, v231
	v_mul_f32_e64 v188, v212, -v186
	v_pk_mul_f32 v[214:215], v[214:215], v[216:217]
	v_pk_mul_f32 v[218:219], v[218:219], v[220:221]
	v_pk_mul_f32 v[222:223], v[222:223], v[224:225]
	v_pk_mul_f32 v[226:227], v[226:227], v[230:231]
	v_pk_fma_f32 v[216:217], v[150:151], v[192:193], v[146:147] op_sel_hi:[1,0,1]
	v_pk_fma_f32 v[220:221], v[152:153], v[192:193], v[148:149] op_sel_hi:[1,0,1]
	v_pk_fma_f32 v[224:225], v[134:135], v[192:193], v[130:131] op_sel_hi:[1,0,1]
	v_pk_fma_f32 v[230:231], v[136:137], v[192:193], v[132:133] op_sel_hi:[1,0,1]
	v_pk_fma_f32 v[216:217], v[12:13], v[190:191], v[216:217] op_sel_hi:[1,0,1]
	v_pk_fma_f32 v[220:221], v[14:15], v[190:191], v[220:221] op_sel_hi:[1,0,1]
	v_pk_fma_f32 v[224:225], v[8:9], v[190:191], v[224:225] op_sel_hi:[1,0,1]
	v_pk_fma_f32 v[230:231], v[10:11], v[190:191], v[230:231] op_sel_hi:[1,0,1]
	v_pk_mul_f32 v[214:215], v[214:215], v[216:217]
	v_pk_mul_f32 v[218:219], v[218:219], v[220:221]
	v_pk_mul_f32 v[222:223], v[222:223], v[224:225]
	v_pk_mul_f32 v[226:227], v[226:227], v[230:231]
	v_cvt_pk_f16_f32 v244, v214, v215
	v_cvt_pk_f16_f32 v245, v218, v219
	v_cvt_pk_f16_f32 v246, v222, v223
	v_cvt_pk_f16_f32 v247, v226, v227
	global_store_dwordx4 v[182:183], v[244:247], off
	v_pk_fma_f32 v[214:215], v[154:155], v[188:189], v[158:159] op_sel_hi:[1,0,1]
	v_pk_fma_f32 v[218:219], v[156:157], v[188:189], v[160:161] op_sel_hi:[1,0,1]
	v_pk_fma_f32 v[222:223], v[138:139], v[188:189], v[142:143] op_sel_hi:[1,0,1]
	v_pk_fma_f32 v[226:227], v[140:141], v[188:189], v[144:145] op_sel_hi:[1,0,1]
	v_pk_fma_f32 v[214:215], v[38:39], v[186:187], v[214:215] op_sel_hi:[1,0,1]
	v_pk_fma_f32 v[218:219], v[40:41], v[186:187], v[218:219] op_sel_hi:[1,0,1]
	v_pk_fma_f32 v[222:223], v[34:35], v[186:187], v[222:223] op_sel_hi:[1,0,1]
	v_pk_fma_f32 v[226:227], v[36:37], v[186:187], v[226:227] op_sel_hi:[1,0,1]
	v_pk_mul_f32 v[216:217], v[214:215], s[100:101] op_sel_hi:[1,0]
	v_pk_mul_f32 v[220:221], v[218:219], s[100:101] op_sel_hi:[1,0]
	v_pk_mul_f32 v[224:225], v[222:223], s[100:101] op_sel_hi:[1,0]
	v_pk_mul_f32 v[230:231], v[226:227], s[100:101] op_sel_hi:[1,0]
	v_exp_f32_e32 v216, v216
	v_exp_f32_e32 v217, v217
	v_exp_f32_e32 v220, v220
	v_exp_f32_e32 v221, v221
	v_exp_f32_e32 v224, v224
	v_exp_f32_e32 v225, v225
	v_exp_f32_e32 v230, v230
	v_exp_f32_e32 v231, v231
	v_pk_add_f32 v[216:217], v[216:217], s[100:101] op_sel:[0,1] op_sel_hi:[1,1]
	v_pk_add_f32 v[220:221], v[220:221], s[100:101] op_sel:[0,1] op_sel_hi:[1,1]
	v_pk_add_f32 v[224:225], v[224:225], s[100:101] op_sel:[0,1] op_sel_hi:[1,1]
	v_pk_add_f32 v[230:231], v[230:231], s[100:101] op_sel:[0,1] op_sel_hi:[1,1]
	v_rcp_f32_e32 v216, v216
	v_rcp_f32_e32 v217, v217
	v_rcp_f32_e32 v220, v220
	v_rcp_f32_e32 v221, v221
	v_rcp_f32_e32 v224, v224
	v_rcp_f32_e32 v225, v225
	v_rcp_f32_e32 v230, v230
	v_rcp_f32_e32 v231, v231
	v_pk_mul_f32 v[214:215], v[214:215], v[216:217]
	v_pk_mul_f32 v[218:219], v[218:219], v[220:221]
	v_pk_mul_f32 v[222:223], v[222:223], v[224:225]
	v_pk_mul_f32 v[226:227], v[226:227], v[230:231]
	v_pk_fma_f32 v[216:217], v[150:151], v[188:189], v[146:147] op_sel_hi:[1,0,1]
	v_pk_fma_f32 v[220:221], v[152:153], v[188:189], v[148:149] op_sel_hi:[1,0,1]
	v_pk_fma_f32 v[224:225], v[134:135], v[188:189], v[130:131] op_sel_hi:[1,0,1]
	v_pk_fma_f32 v[230:231], v[136:137], v[188:189], v[132:133] op_sel_hi:[1,0,1]
	v_pk_fma_f32 v[216:217], v[4:5], v[186:187], v[216:217] op_sel_hi:[1,0,1]
	v_pk_fma_f32 v[220:221], v[6:7], v[186:187], v[220:221] op_sel_hi:[1,0,1]
	v_pk_fma_f32 v[224:225], v[0:1], v[186:187], v[224:225] op_sel_hi:[1,0,1]
	v_pk_fma_f32 v[230:231], v[2:3], v[186:187], v[230:231] op_sel_hi:[1,0,1]
	v_pk_mul_f32 v[214:215], v[214:215], v[216:217]
	v_pk_mul_f32 v[218:219], v[218:219], v[220:221]
	v_pk_mul_f32 v[222:223], v[222:223], v[224:225]
	v_pk_mul_f32 v[226:227], v[226:227], v[230:231]
	v_cvt_pk_f16_f32 v244, v214, v215
	v_cvt_pk_f16_f32 v245, v218, v219
	v_cvt_pk_f16_f32 v246, v222, v223
	v_cvt_pk_f16_f32 v247, v226, v227
	global_store_dwordx4 v[184:185], v[244:247], off
	s_cmp_eq_u32 s15, 0
	s_cbranch_scc0 .LBB0_212

; __global__ void __launch_bounds__(512, 2) mega_fwd(P p) {
	.amdhsa_kernel _Z8mega_fwd1P
		.amdhsa_group_segment_fixed_size 0
		.amdhsa_private_segment_fixed_size 0
		.amdhsa_kernarg_size 480
		.amdhsa_user_sgpr_count 2
		.amdhsa_user_sgpr_dispatch_ptr 0
		.amdhsa_user_sgpr_queue_ptr 0
		.amdhsa_user_sgpr_kernarg_segment_ptr 1
		.amdhsa_user_sgpr_dispatch_id 0
		.amdhsa_user_sgpr_kernarg_preload_length 0
		.amdhsa_user_sgpr_kernarg_preload_offset 0
		.amdhsa_user_sgpr_private_segment_size 0
		.amdhsa_uses_dynamic_stack 0
		.amdhsa_enable_private_segment 0
		.amdhsa_system_sgpr_workgroup_id_x 1
		.amdhsa_system_sgpr_workgroup_id_y 0
		.amdhsa_system_sgpr_workgroup_id_z 0
		.amdhsa_system_sgpr_workgroup_info 0
		.amdhsa_system_vgpr_workitem_id 2
		.amdhsa_next_free_vgpr 256
		.amdhsa_next_free_sgpr 102
		.amdhsa_accum_offset 256
		.amdhsa_reserve_vcc 1
		.amdhsa_float_round_mode_32 0
		.amdhsa_float_round_mode_16_64 0
		.amdhsa_float_denorm_mode_32 3
		.amdhsa_float_denorm_mode_16_64 3
		.amdhsa_dx10_clamp 1
		.amdhsa_ieee_mode 1
		.amdhsa_fp16_overflow 0
		.amdhsa_tg_split 0
		.amdhsa_exception_fp_ieee_invalid_op 0
		.amdhsa_exception_fp_denorm_src 0
		.amdhsa_exception_fp_ieee_div_zero 0
		.amdhsa_exception_fp_ieee_overflow 0
		.amdhsa_exception_fp_ieee_underflow 0
		.amdhsa_exception_fp_ieee_inexact 0
		.amdhsa_exception_int_div_zero 0
	.end_amdhsa_kernel
